# v25 + s_setprio 3 while a wave issues its K-step LDS-DMA loads (the latency-critical part), back to 0 before the fragment reads
# speedup vs baseline: 1.0151x; 1.0014x over previous
.LBB0_303:
	s_setprio 3
	s_and_b32 s1, s0, 0x2000
	s_xor_b32 s8, s1, 0x2000
	s_lshl_b32 s101, s8, 1
	s_add_u32 s101, s101, s100
	s_add_u32 m0, s101, 0x0
	s_nop 0
	global_load_lds_dwordx4 v[184:185], off
	s_add_u32 m0, s101, 0x1000
	v_lshl_add_u64 v[184:185], v[184:185], 0, vcc
	global_load_lds_dwordx4 v[186:187], off
	s_add_u32 m0, s101, 0x2000
	v_lshl_add_u64 v[186:187], v[186:187], 0, vcc
	global_load_lds_dwordx4 v[188:189], off
	s_add_u32 m0, s101, 0x3000
	v_lshl_add_u64 v[188:189], v[188:189], 0, vcc
	global_load_lds_dwordx4 v[190:191], off
	s_add_u32 m0, s101, 0x8000
	v_lshl_add_u64 v[190:191], v[190:191], 0, vcc
	global_load_lds_dwordx4 v[192:193], off
	s_add_u32 m0, s101, 0x9000
	v_lshl_add_u64 v[192:193], v[192:193], 0, vcc
	global_load_lds_dwordx4 v[194:195], off
	s_add_u32 m0, s101, 0xa000
	v_lshl_add_u64 v[194:195], v[194:195], 0, vcc
	global_load_lds_dwordx4 v[196:197], off
	s_add_u32 m0, s101, 0xb000
	v_lshl_add_u64 v[196:197], v[196:197], 0, vcc
	global_load_lds_dwordx4 v[198:199], off
	s_setprio 0
	v_lshl_add_u64 v[198:199], v[198:199], 0, vcc
	s_lshl_b32 s1, s1, 1
	v_add_u32_e32 v82, s1, v86
	v_add_u32_e32 v83, s1, v85
	v_add_u32_e32 v95, v82, v93
	ds_read_b128 v[96:99], v95
	ds_read_b128 v[100:103], v95 offset:2048
	ds_read_b128 v[120:123], v95 offset:4096
	ds_read_b128 v[124:127], v95 offset:6144
	v_add_u32_e32 v95, v83, v93
	ds_read_b128 v[128:131], v95 offset:32768
	ds_read_b128 v[132:135], v95 offset:34816
	ds_read_b128 v[136:139], v95 offset:36864
	ds_read_b128 v[140:143], v95 offset:38912
	s_setprio 1
	s_waitcnt lgkmcnt(0)
	v_mfma_f32_16x16x32_bf16 v[60:63], v[128:131], v[96:99], v[60:63]
	v_mfma_f32_16x16x32_bf16 v[56:59], v[132:135], v[96:99], v[56:59]
	v_mfma_f32_16x16x32_bf16 v[52:55], v[136:139], v[96:99], v[52:55]
	v_mfma_f32_16x16x32_bf16 v[48:51], v[140:143], v[96:99], v[48:51]
	v_mfma_f32_16x16x32_bf16 v[44:47], v[128:131], v[100:103], v[44:47]
	v_mfma_f32_16x16x32_bf16 v[40:43], v[132:135], v[100:103], v[40:43]
	v_mfma_f32_16x16x32_bf16 v[36:39], v[136:139], v[100:103], v[36:39]
	v_mfma_f32_16x16x32_bf16 v[32:35], v[140:143], v[100:103], v[32:35]
	v_mfma_f32_16x16x32_bf16 v[28:31], v[128:131], v[120:123], v[28:31]
	v_mfma_f32_16x16x32_bf16 v[24:27], v[132:135], v[120:123], v[24:27]
	v_mfma_f32_16x16x32_bf16 v[20:23], v[136:139], v[120:123], v[20:23]
	v_mfma_f32_16x16x32_bf16 v[16:19], v[140:143], v[120:123], v[16:19]
	v_mfma_f32_16x16x32_bf16 v[12:15], v[128:131], v[124:127], v[12:15]
	v_mfma_f32_16x16x32_bf16 v[8:11], v[132:135], v[124:127], v[8:11]
	v_mfma_f32_16x16x32_bf16 v[4:7], v[136:139], v[124:127], v[4:7]
	v_mfma_f32_16x16x32_bf16 v[0:3], v[140:143], v[124:127], v[0:3]
	s_setprio 0
	v_add_u32_e32 v82, v82, v94
	ds_read_b128 v[96:99], v82
	ds_read_b128 v[100:103], v82 offset:2048
	ds_read_b128 v[120:123], v82 offset:4096
	ds_read_b128 v[124:127], v82 offset:6144
	v_add_u32_e32 v82, v83, v94
	ds_read_b128 v[128:131], v82 offset:32768
	ds_read_b128 v[132:135], v82 offset:34816
	ds_read_b128 v[136:139], v82 offset:36864
	ds_read_b128 v[140:143], v82 offset:38912
	s_setprio 1
	s_waitcnt lgkmcnt(0)
	v_mfma_f32_16x16x32_bf16 v[60:63], v[128:131], v[96:99], v[60:63]
	v_mfma_f32_16x16x32_bf16 v[56:59], v[132:135], v[96:99], v[56:59]
	v_mfma_f32_16x16x32_bf16 v[52:55], v[136:139], v[96:99], v[52:55]
	v_mfma_f32_16x16x32_bf16 v[48:51], v[140:143], v[96:99], v[48:51]
	v_mfma_f32_16x16x32_bf16 v[44:47], v[128:131], v[100:103], v[44:47]
	v_mfma_f32_16x16x32_bf16 v[40:43], v[132:135], v[100:103], v[40:43]
	v_mfma_f32_16x16x32_bf16 v[36:39], v[136:139], v[100:103], v[36:39]
	v_mfma_f32_16x16x32_bf16 v[32:35], v[140:143], v[100:103], v[32:35]
	v_mfma_f32_16x16x32_bf16 v[28:31], v[128:131], v[120:123], v[28:31]
	v_mfma_f32_16x16x32_bf16 v[24:27], v[132:135], v[120:123], v[24:27]
	v_mfma_f32_16x16x32_bf16 v[20:23], v[136:139], v[120:123], v[20:23]
	v_mfma_f32_16x16x32_bf16 v[16:19], v[140:143], v[120:123], v[16:19]
	v_mfma_f32_16x16x32_bf16 v[12:15], v[128:131], v[124:127], v[12:15]
	v_mfma_f32_16x16x32_bf16 v[8:11], v[132:135], v[124:127], v[8:11]
	v_mfma_f32_16x16x32_bf16 v[4:7], v[136:139], v[124:127], v[4:7]
	v_mfma_f32_16x16x32_bf16 v[0:3], v[140:143], v[124:127], v[0:3]
	s_setprio 0
	s_addk_i32 s0, 0x2000
	s_waitcnt vmcnt(0)
	s_add_u32 s20, s20, 0x80
	s_addc_u32 s21, s21, 0
	s_cmpk_lg_i32 s20, 0x780
	s_waitcnt vmcnt(0)
	s_barrier
	s_cbranch_scc1 .LBB0_303
	ds_read_b128 v[78:81], v89 offset:55296
	ds_read_b128 v[96:99], v89 offset:53248
	ds_read_b128 v[100:103], v89 offset:51200
	ds_read_b128 v[120:123], v89 offset:49152
	ds_read_b128 v[124:127], v90 offset:22528
	ds_read_b128 v[128:131], v90 offset:20480
	ds_read_b128 v[132:135], v90 offset:18432
	ds_read_b128 v[136:139], v90 offset:16384
	s_setprio 1
	s_waitcnt lgkmcnt(0)
	v_mfma_f32_16x16x32_bf16 v[60:63], v[120:123], v[136:139], v[60:63]
	v_mfma_f32_16x16x32_bf16 v[56:59], v[100:103], v[136:139], v[56:59]
	v_mfma_f32_16x16x32_bf16 v[52:55], v[96:99], v[136:139], v[52:55]
	v_mfma_f32_16x16x32_bf16 v[48:51], v[78:81], v[136:139], v[48:51]
	v_mfma_f32_16x16x32_bf16 v[44:47], v[120:123], v[132:135], v[44:47]
	v_mfma_f32_16x16x32_bf16 v[40:43], v[100:103], v[132:135], v[40:43]
	v_mfma_f32_16x16x32_bf16 v[36:39], v[96:99], v[132:135], v[36:39]
	v_mfma_f32_16x16x32_bf16 v[32:35], v[78:81], v[132:135], v[32:35]
	v_mfma_f32_16x16x32_bf16 v[28:31], v[120:123], v[128:131], v[28:31]
	v_mfma_f32_16x16x32_bf16 v[24:27], v[100:103], v[128:131], v[24:27]
	v_mfma_f32_16x16x32_bf16 v[20:23], v[96:99], v[128:131], v[20:23]
	v_mfma_f32_16x16x32_bf16 v[16:19], v[78:81], v[128:131], v[16:19]
	v_mfma_f32_16x16x32_bf16 v[12:15], v[120:123], v[124:127], v[12:15]
	v_mfma_f32_16x16x32_bf16 v[8:11], v[100:103], v[124:127], v[8:11]
	v_mfma_f32_16x16x32_bf16 v[4:7], v[96:99], v[124:127], v[4:7]
	v_mfma_f32_16x16x32_bf16 v[0:3], v[78:81], v[124:127], v[0:3]
	s_setprio 0
	ds_read_b128 v[78:81], v91 offset:16384
	ds_read_b128 v[96:99], v91 offset:18432
	ds_read_b128 v[100:103], v91 offset:20480
	ds_read_b128 v[120:123], v91 offset:22528
	ds_read_b128 v[124:127], v92 offset:49152
	ds_read_b128 v[128:131], v92 offset:51200
	ds_read_b128 v[132:135], v92 offset:53248
	ds_read_b128 v[136:139], v92 offset:55296
	s_setprio 1
	s_waitcnt lgkmcnt(3)
	v_mfma_f32_16x16x32_bf16 v[60:63], v[124:127], v[78:81], v[60:63]
	s_waitcnt lgkmcnt(2)
	v_mfma_f32_16x16x32_bf16 v[56:59], v[128:131], v[78:81], v[56:59]
	s_waitcnt lgkmcnt(1)
	v_mfma_f32_16x16x32_bf16 v[52:55], v[132:135], v[78:81], v[52:55]
	s_waitcnt lgkmcnt(0)
	v_mfma_f32_16x16x32_bf16 v[48:51], v[136:139], v[78:81], v[48:51]
	v_mfma_f32_16x16x32_bf16 v[44:47], v[124:127], v[96:99], v[44:47]
	v_mfma_f32_16x16x32_bf16 v[40:43], v[128:131], v[96:99], v[40:43]
	v_mfma_f32_16x16x32_bf16 v[36:39], v[132:135], v[96:99], v[36:39]
	v_mfma_f32_16x16x32_bf16 v[32:35], v[136:139], v[96:99], v[32:35]
	v_mfma_f32_16x16x32_bf16 v[28:31], v[124:127], v[100:103], v[28:31]
	v_mfma_f32_16x16x32_bf16 v[24:27], v[128:131], v[100:103], v[24:27]
	v_mfma_f32_16x16x32_bf16 v[20:23], v[132:135], v[100:103], v[20:23]
	v_mfma_f32_16x16x32_bf16 v[16:19], v[136:139], v[100:103], v[16:19]
	v_mfma_f32_16x16x32_bf16 v[12:15], v[124:127], v[120:123], v[12:15]
	v_mfma_f32_16x16x32_bf16 v[8:11], v[128:131], v[120:123], v[8:11]
	v_mfma_f32_16x16x32_bf16 v[4:7], v[132:135], v[120:123], v[4:7]
	v_mfma_f32_16x16x32_bf16 v[0:3], v[136:139], v[120:123], v[0:3]
	s_setprio 0
	s_waitcnt vmcnt(0)
	s_cmp_lt_i32 s10, 32
	s_mov_b64 s[0:1], -1
	s_barrier
	s_cbranch_scc1 .LBB0_594
	s_cmp_eq_u32 s10, 32
	s_cselect_b64 s[0:1], -1, 0
	s_and_b64 vcc, exec, s[0:1]
	v_mov_b32_e32 v79, v63
	v_mov_b32_e32 v82, v62
	v_mov_b32_e32 v83, v61
	v_mov_b32_e32 v95, v60
	s_cbranch_vccz .LBB0_323
	v_cmp_nlt_f32_e64 s[8:9], |v60|, s33
	s_and_saveexec_b64 s[12:13], s[8:9]
	s_xor_b64 s[8:9], exec, s[12:13]
	s_cbranch_execz .LBB0_308
	v_add_f32_e64 v78, |v60|, |v60|
	v_mul_f32_e32 v79, 0x3fb8aa3b, v78
	v_rndne_f32_e32 v80, v79
	s_mov_b32 s11, 0x3fb8aa3b
	v_sub_f32_e32 v81, v79, v80
	v_fma_f32 v79, v78, s11, -v79
	v_fmac_f32_e32 v79, 0x32a5705f, v78
	v_add_f32_e32 v79, v81, v79
	v_cvt_i32_f32_e32 v80, v80
	v_exp_f32_e32 v79, v79
	s_mov_b32 s11, 0xc2ce8ed0
	v_cmp_ngt_f32_e32 vcc, s11, v78
	s_mov_b32 s11, 0x42b17218
	v_ldexp_f32 v79, v79, v80
	v_cndmask_b32_e32 v79, 0, v79, vcc
	v_cmp_nlt_f32_e32 vcc, s11, v78
	s_nop 1
	v_cndmask_b32_e32 v78, v112, v79, vcc
	v_add_f32_e32 v78, 1.0, v78
	v_rcp_f32_e32 v78, v78
	s_nop 0
	v_fma_f32 v78, v78, -2.0, 1.0

.LBB0_882:
	s_setprio 3
	s_and_b32 s6, s0, 0x2000
	s_xor_b32 s8, s6, 0x2000
	s_lshl_b32 s101, s8, 1
	s_add_u32 s101, s101, s100
	s_add_u32 m0, s101, 0x0
	s_nop 0
	global_load_lds_dwordx4 v[184:185], off
	s_add_u32 m0, s101, 0x1000
	v_lshl_add_u64 v[184:185], v[184:185], 0, vcc
	global_load_lds_dwordx4 v[186:187], off
	s_add_u32 m0, s101, 0x2000
	v_lshl_add_u64 v[186:187], v[186:187], 0, vcc
	global_load_lds_dwordx4 v[188:189], off
	s_add_u32 m0, s101, 0x3000
	v_lshl_add_u64 v[188:189], v[188:189], 0, vcc
	global_load_lds_dwordx4 v[190:191], off
	s_add_u32 m0, s101, 0x8000
	v_lshl_add_u64 v[190:191], v[190:191], 0, vcc
	global_load_lds_dwordx4 v[192:193], off
	s_add_u32 m0, s101, 0x9000
	v_lshl_add_u64 v[192:193], v[192:193], 0, vcc
	global_load_lds_dwordx4 v[194:195], off
	s_add_u32 m0, s101, 0xa000
	v_lshl_add_u64 v[194:195], v[194:195], 0, vcc
	global_load_lds_dwordx4 v[196:197], off
	s_add_u32 m0, s101, 0xb000
	v_lshl_add_u64 v[196:197], v[196:197], 0, vcc
	global_load_lds_dwordx4 v[198:199], off
	s_setprio 0
	v_lshl_add_u64 v[198:199], v[198:199], 0, vcc
	s_lshl_b32 s6, s6, 1
	v_add_u32_e32 v102, s6, v90
	v_add_u32_e32 v103, s6, v71
	v_add_u32_e32 v128, v102, v96
	v_add_u32_e32 v144, v103, v96
	ds_read_b128 v[98:101], v128
	ds_read_b128 v[120:123], v128 offset:2048
	ds_read_b128 v[124:127], v128 offset:4096
	ds_read_b128 v[128:131], v128 offset:6144
	ds_read_b128 v[132:135], v144 offset:32768
	ds_read_b128 v[136:139], v144 offset:34816
	ds_read_b128 v[140:143], v144 offset:36864
	ds_read_b128 v[144:147], v144 offset:38912
	s_setprio 1
	s_waitcnt lgkmcnt(0)
	v_mfma_f32_16x16x32_bf16 v[60:63], v[132:135], v[98:101], v[60:63]
	v_mfma_f32_16x16x32_bf16 v[56:59], v[136:139], v[98:101], v[56:59]
	v_mfma_f32_16x16x32_bf16 v[52:55], v[140:143], v[98:101], v[52:55]
	v_mfma_f32_16x16x32_bf16 v[48:51], v[144:147], v[98:101], v[48:51]
	v_mfma_f32_16x16x32_bf16 v[44:47], v[132:135], v[120:123], v[44:47]
	v_mfma_f32_16x16x32_bf16 v[40:43], v[136:139], v[120:123], v[40:43]
	v_mfma_f32_16x16x32_bf16 v[36:39], v[140:143], v[120:123], v[36:39]
	v_mfma_f32_16x16x32_bf16 v[32:35], v[144:147], v[120:123], v[32:35]
	v_mfma_f32_16x16x32_bf16 v[28:31], v[132:135], v[124:127], v[28:31]
	v_mfma_f32_16x16x32_bf16 v[24:27], v[136:139], v[124:127], v[24:27]
	v_mfma_f32_16x16x32_bf16 v[20:23], v[140:143], v[124:127], v[20:23]
	v_mfma_f32_16x16x32_bf16 v[16:19], v[144:147], v[124:127], v[16:19]
	v_mfma_f32_16x16x32_bf16 v[12:15], v[132:135], v[128:131], v[12:15]
	v_mfma_f32_16x16x32_bf16 v[8:11], v[136:139], v[128:131], v[8:11]
	v_mfma_f32_16x16x32_bf16 v[4:7], v[140:143], v[128:131], v[4:7]
	v_mfma_f32_16x16x32_bf16 v[0:3], v[144:147], v[128:131], v[0:3]
	s_setprio 0
	v_add_u32_e32 v102, v102, v97
	ds_read_b128 v[98:101], v102
	ds_read_b128 v[120:123], v102 offset:2048
	ds_read_b128 v[124:127], v102 offset:4096
	ds_read_b128 v[128:131], v102 offset:6144
	v_add_u32_e32 v102, v103, v97
	ds_read_b128 v[132:135], v102 offset:32768
	ds_read_b128 v[136:139], v102 offset:34816
	ds_read_b128 v[140:143], v102 offset:36864
	ds_read_b128 v[144:147], v102 offset:38912
	s_setprio 1
	s_waitcnt lgkmcnt(0)
	v_mfma_f32_16x16x32_bf16 v[60:63], v[132:135], v[98:101], v[60:63]
	v_mfma_f32_16x16x32_bf16 v[56:59], v[136:139], v[98:101], v[56:59]
	v_mfma_f32_16x16x32_bf16 v[52:55], v[140:143], v[98:101], v[52:55]
	v_mfma_f32_16x16x32_bf16 v[48:51], v[144:147], v[98:101], v[48:51]
	v_mfma_f32_16x16x32_bf16 v[44:47], v[132:135], v[120:123], v[44:47]
	v_mfma_f32_16x16x32_bf16 v[40:43], v[136:139], v[120:123], v[40:43]
	v_mfma_f32_16x16x32_bf16 v[36:39], v[140:143], v[120:123], v[36:39]
	v_mfma_f32_16x16x32_bf16 v[32:35], v[144:147], v[120:123], v[32:35]
	v_mfma_f32_16x16x32_bf16 v[28:31], v[132:135], v[124:127], v[28:31]
	v_mfma_f32_16x16x32_bf16 v[24:27], v[136:139], v[124:127], v[24:27]
	v_mfma_f32_16x16x32_bf16 v[20:23], v[140:143], v[124:127], v[20:23]
	v_mfma_f32_16x16x32_bf16 v[16:19], v[144:147], v[124:127], v[16:19]
	v_mfma_f32_16x16x32_bf16 v[12:15], v[132:135], v[128:131], v[12:15]
	v_mfma_f32_16x16x32_bf16 v[8:11], v[136:139], v[128:131], v[8:11]
	v_mfma_f32_16x16x32_bf16 v[4:7], v[140:143], v[128:131], v[4:7]
	v_mfma_f32_16x16x32_bf16 v[0:3], v[144:147], v[128:131], v[0:3]
	s_setprio 0
	s_waitcnt vmcnt(0)
	s_add_u32 s36, s36, 0x80
	s_addc_u32 s37, s37, 0
	s_addk_i32 s0, 0x2000
	s_cmpk_lg_i32 s36, 0x780
	s_waitcnt vmcnt(0)
	s_barrier
	s_cbranch_scc1 .LBB0_882
	ds_read_b128 v[86:89], v92 offset:16384
	ds_read_b128 v[98:101], v92 offset:18432
	ds_read_b128 v[120:123], v92 offset:20480
	ds_read_b128 v[124:127], v92 offset:22528
	ds_read_b128 v[128:131], v93 offset:49152
	ds_read_b128 v[132:135], v93 offset:51200
	ds_read_b128 v[136:139], v93 offset:53248
	ds_read_b128 v[140:143], v93 offset:55296
	s_setprio 1
	s_waitcnt lgkmcnt(3)
	v_mfma_f32_16x16x32_bf16 v[60:63], v[128:131], v[86:89], v[60:63]
	s_waitcnt lgkmcnt(2)
	v_mfma_f32_16x16x32_bf16 v[56:59], v[132:135], v[86:89], v[56:59]
	s_waitcnt lgkmcnt(1)
	v_mfma_f32_16x16x32_bf16 v[52:55], v[136:139], v[86:89], v[52:55]
	s_waitcnt lgkmcnt(0)
	v_mfma_f32_16x16x32_bf16 v[48:51], v[140:143], v[86:89], v[48:51]
	v_mfma_f32_16x16x32_bf16 v[40:43], v[132:135], v[98:101], v[40:43]
	v_mfma_f32_16x16x32_bf16 v[36:39], v[136:139], v[98:101], v[36:39]
	v_mfma_f32_16x16x32_bf16 v[32:35], v[140:143], v[98:101], v[32:35]
	v_mfma_f32_16x16x32_bf16 v[20:23], v[136:139], v[120:123], v[20:23]
	v_mfma_f32_16x16x32_bf16 v[16:19], v[140:143], v[120:123], v[16:19]
	v_mfma_f32_16x16x32_bf16 v[0:3], v[140:143], v[124:127], v[0:3]
	v_mfma_f32_16x16x32_bf16 v[86:89], v[128:131], v[98:101], v[44:47]
	v_mfma_f32_16x16x32_bf16 v[98:101], v[128:131], v[120:123], v[28:31]
	v_mfma_f32_16x16x32_bf16 v[144:147], v[132:135], v[120:123], v[24:27]
	v_mfma_f32_16x16x32_bf16 v[120:123], v[128:131], v[124:127], v[12:15]
	v_mfma_f32_16x16x32_bf16 v[128:131], v[132:135], v[124:127], v[8:11]
	v_mfma_f32_16x16x32_bf16 v[132:135], v[136:139], v[124:127], v[4:7]
	s_setprio 0
	s_nop 1
	ds_read_b128 v[4:7], v94 offset:16384
	ds_read_b128 v[8:11], v94 offset:18432
	ds_read_b128 v[124:127], v94 offset:20480
	ds_read_b128 v[136:139], v94 offset:22528
	ds_read_b128 v[140:143], v95 offset:49152
	ds_read_b128 v[148:151], v95 offset:51200
	ds_read_b128 v[152:155], v95 offset:53248
	ds_read_b128 v[156:159], v95 offset:55296
	s_setprio 1
	s_waitcnt lgkmcnt(3)
	v_mfma_f32_16x16x32_bf16 v[60:63], v[140:143], v[4:7], v[60:63]
	s_waitcnt lgkmcnt(2)
	v_mfma_f32_16x16x32_bf16 v[44:47], v[148:151], v[4:7], v[56:59]
	s_waitcnt lgkmcnt(1)
	v_mfma_f32_16x16x32_bf16 v[28:31], v[152:155], v[4:7], v[52:55]
	s_waitcnt lgkmcnt(0)
	v_mfma_f32_16x16x32_bf16 v[12:15], v[156:159], v[4:7], v[48:51]
	v_mfma_f32_16x16x32_bf16 v[56:59], v[140:143], v[8:11], v[86:89]
	v_mfma_f32_16x16x32_bf16 v[40:43], v[148:151], v[8:11], v[40:43]
	v_mfma_f32_16x16x32_bf16 v[24:27], v[152:155], v[8:11], v[36:39]
	v_mfma_f32_16x16x32_bf16 v[8:11], v[156:159], v[8:11], v[32:35]
	v_mfma_f32_16x16x32_bf16 v[52:55], v[140:143], v[124:127], v[98:101]
	v_mfma_f32_16x16x32_bf16 v[36:39], v[148:151], v[124:127], v[144:147]
	v_mfma_f32_16x16x32_bf16 v[20:23], v[152:155], v[124:127], v[20:23]
	v_mfma_f32_16x16x32_bf16 v[4:7], v[156:159], v[124:127], v[16:19]
	v_mfma_f32_16x16x32_bf16 v[48:51], v[140:143], v[136:139], v[120:123]
	v_mfma_f32_16x16x32_bf16 v[32:35], v[148:151], v[136:139], v[128:131]
	v_mfma_f32_16x16x32_bf16 v[16:19], v[152:155], v[136:139], v[132:135]
	v_mfma_f32_16x16x32_bf16 v[0:3], v[156:159], v[136:139], v[0:3]
	s_setprio 0
	s_waitcnt vmcnt(0)
	s_cmpk_gt_i32 s1, 0x7f
	s_barrier
	s_cbranch_scc0 .LBB0_885
	s_add_i32 s0, s24, 0xffffc000
	s_lshr_b32 s0, s0, 8
	v_readlane_b32 s6, v180, 24
	s_add_i32 s6, s0, s6
	s_and_b32 s10, s24, 0x80
	s_lshl_b64 s[8:9], s[6:7], 8
	v_readlane_b32 s36, v182, 19
	s_or_b32 s8, s8, s10
	s_mov_b64 s[10:11], 0
	v_readlane_b32 s37, v182, 20
	s_branch .LBB0_886

.LBB0_895:
	s_setprio 3
	s_and_b32 s0, s10, 0x2000
	s_xor_b32 s1, s0, 0x2000
	s_lshl_b32 s101, s1, 1
	s_add_u32 s101, s101, s100
	s_add_u32 m0, s101, 0x0
	s_nop 0
	global_load_lds_dwordx4 v[184:185], off
	s_add_u32 m0, s101, 0x1000
	v_lshl_add_u64 v[184:185], v[184:185], 0, vcc
	global_load_lds_dwordx4 v[186:187], off
	s_add_u32 m0, s101, 0x2000
	v_lshl_add_u64 v[186:187], v[186:187], 0, vcc
	global_load_lds_dwordx4 v[188:189], off
	s_add_u32 m0, s101, 0x3000
	v_lshl_add_u64 v[188:189], v[188:189], 0, vcc
	global_load_lds_dwordx4 v[190:191], off
	s_add_u32 m0, s101, 0x8000
	v_lshl_add_u64 v[190:191], v[190:191], 0, vcc
	global_load_lds_dwordx4 v[192:193], off
	s_add_u32 m0, s101, 0x9000
	v_lshl_add_u64 v[192:193], v[192:193], 0, vcc
	global_load_lds_dwordx4 v[194:195], off
	s_add_u32 m0, s101, 0xa000
	v_lshl_add_u64 v[194:195], v[194:195], 0, vcc
	global_load_lds_dwordx4 v[196:197], off
	s_add_u32 m0, s101, 0xb000
	v_lshl_add_u64 v[196:197], v[196:197], 0, vcc
	global_load_lds_dwordx4 v[198:199], off
	s_setprio 0
	v_lshl_add_u64 v[198:199], v[198:199], 0, vcc
	s_lshl_b32 s0, s0, 1
	v_add_u32_e32 v68, s0, v120
	v_add_u32_e32 v102, s0, v121
	v_add_u32_e32 v98, v68, v133
	v_add_u32_e32 v103, v102, v133
	ds_read_b128 v[86:89], v98
	ds_read_b128 v[90:93], v98 offset:2048
	ds_read_b128 v[94:97], v98 offset:4096
	ds_read_b128 v[98:101], v98 offset:6144
	ds_read_b128 v[144:147], v103 offset:32768
	ds_read_b128 v[148:151], v103 offset:34816
	ds_read_b128 v[152:155], v103 offset:36864
	ds_read_b128 v[156:159], v103 offset:38912
	s_setprio 1
	s_waitcnt lgkmcnt(0)
	v_mfma_f32_16x16x32_bf16 v[60:63], v[86:89], v[144:147], v[60:63]
	v_mfma_f32_16x16x32_bf16 v[56:59], v[86:89], v[148:151], v[56:59]
	v_mfma_f32_16x16x32_bf16 v[52:55], v[86:89], v[152:155], v[52:55]
	v_mfma_f32_16x16x32_bf16 v[48:51], v[86:89], v[156:159], v[48:51]
	v_mfma_f32_16x16x32_bf16 v[44:47], v[90:93], v[144:147], v[44:47]
	v_mfma_f32_16x16x32_bf16 v[40:43], v[90:93], v[148:151], v[40:43]
	v_mfma_f32_16x16x32_bf16 v[36:39], v[90:93], v[152:155], v[36:39]
	v_mfma_f32_16x16x32_bf16 v[32:35], v[90:93], v[156:159], v[32:35]
	v_mfma_f32_16x16x32_bf16 v[28:31], v[94:97], v[144:147], v[28:31]
	v_mfma_f32_16x16x32_bf16 v[24:27], v[94:97], v[148:151], v[24:27]
	v_mfma_f32_16x16x32_bf16 v[20:23], v[94:97], v[152:155], v[20:23]
	v_mfma_f32_16x16x32_bf16 v[16:19], v[94:97], v[156:159], v[16:19]
	v_mfma_f32_16x16x32_bf16 v[12:15], v[98:101], v[144:147], v[12:15]
	v_mfma_f32_16x16x32_bf16 v[8:11], v[98:101], v[148:151], v[8:11]
	v_mfma_f32_16x16x32_bf16 v[4:7], v[98:101], v[152:155], v[4:7]
	v_mfma_f32_16x16x32_bf16 v[0:3], v[98:101], v[156:159], v[0:3]
	s_setprio 0
	v_add_u32_e32 v68, v68, v134
	ds_read_b128 v[86:89], v68
	ds_read_b128 v[90:93], v68 offset:2048
	ds_read_b128 v[94:97], v68 offset:4096
	ds_read_b128 v[98:101], v68 offset:6144
	v_add_u32_e32 v68, v102, v134
	ds_read_b128 v[144:147], v68 offset:32768
	ds_read_b128 v[148:151], v68 offset:34816
	ds_read_b128 v[152:155], v68 offset:36864
	ds_read_b128 v[156:159], v68 offset:38912
	s_setprio 1
	s_waitcnt lgkmcnt(0)
	v_mfma_f32_16x16x32_bf16 v[60:63], v[86:89], v[144:147], v[60:63]
	v_mfma_f32_16x16x32_bf16 v[56:59], v[86:89], v[148:151], v[56:59]
	v_mfma_f32_16x16x32_bf16 v[52:55], v[86:89], v[152:155], v[52:55]
	v_mfma_f32_16x16x32_bf16 v[48:51], v[86:89], v[156:159], v[48:51]
	v_mfma_f32_16x16x32_bf16 v[44:47], v[90:93], v[144:147], v[44:47]
	v_mfma_f32_16x16x32_bf16 v[40:43], v[90:93], v[148:151], v[40:43]
	v_mfma_f32_16x16x32_bf16 v[36:39], v[90:93], v[152:155], v[36:39]
	v_mfma_f32_16x16x32_bf16 v[32:35], v[90:93], v[156:159], v[32:35]
	v_mfma_f32_16x16x32_bf16 v[28:31], v[94:97], v[144:147], v[28:31]
	v_mfma_f32_16x16x32_bf16 v[24:27], v[94:97], v[148:151], v[24:27]
	v_mfma_f32_16x16x32_bf16 v[20:23], v[94:97], v[152:155], v[20:23]
	v_mfma_f32_16x16x32_bf16 v[16:19], v[94:97], v[156:159], v[16:19]
	v_mfma_f32_16x16x32_bf16 v[12:15], v[98:101], v[144:147], v[12:15]
	v_mfma_f32_16x16x32_bf16 v[8:11], v[98:101], v[148:151], v[8:11]
	v_mfma_f32_16x16x32_bf16 v[4:7], v[98:101], v[152:155], v[4:7]
	v_mfma_f32_16x16x32_bf16 v[0:3], v[98:101], v[156:159], v[0:3]
	s_setprio 0
	s_addk_i32 s10, 0x2000
	s_waitcnt vmcnt(0)
	s_add_u32 s36, s36, 0x80
	s_addc_u32 s37, s37, 0
	s_cmpk_lg_i32 s36, 0x780
	s_waitcnt vmcnt(0)
	s_barrier
	s_cbranch_scc1 .LBB0_895
	ds_read_b128 v[82:85], v122 offset:55296
	ds_read_b128 v[86:89], v122 offset:53248
	ds_read_b128 v[90:93], v122 offset:51200
	ds_read_b128 v[94:97], v122 offset:49152
	ds_read_b128 v[98:101], v123 offset:22528
	ds_read_b128 v[144:147], v123 offset:20480
	ds_read_b128 v[148:151], v123 offset:18432
	ds_read_b128 v[152:155], v123 offset:16384
	s_setprio 1
	s_waitcnt lgkmcnt(0)
	v_mfma_f32_16x16x32_bf16 v[60:63], v[152:155], v[94:97], v[60:63]
	v_mfma_f32_16x16x32_bf16 v[52:55], v[152:155], v[86:89], v[52:55]
	v_mfma_f32_16x16x32_bf16 v[48:51], v[152:155], v[82:85], v[48:51]
	v_mfma_f32_16x16x32_bf16 v[44:47], v[148:151], v[94:97], v[44:47]
	v_mfma_f32_16x16x32_bf16 v[40:43], v[148:151], v[90:93], v[40:43]
	v_mfma_f32_16x16x32_bf16 v[36:39], v[148:151], v[86:89], v[36:39]
	v_mfma_f32_16x16x32_bf16 v[32:35], v[148:151], v[82:85], v[32:35]
	v_mfma_f32_16x16x32_bf16 v[4:7], v[98:101], v[86:89], v[4:7]
	v_mfma_f32_16x16x32_bf16 v[156:159], v[152:155], v[90:93], v[56:59]
	v_mfma_f32_16x16x32_bf16 v[148:151], v[144:147], v[94:97], v[28:31]
	v_mfma_f32_16x16x32_bf16 v[152:155], v[144:147], v[90:93], v[24:27]
	v_mfma_f32_16x16x32_bf16 v[160:163], v[144:147], v[86:89], v[20:23]
	v_mfma_f32_16x16x32_bf16 v[144:147], v[144:147], v[82:85], v[16:19]
	v_mfma_f32_16x16x32_bf16 v[94:97], v[98:101], v[94:97], v[12:15]
	v_mfma_f32_16x16x32_bf16 v[90:93], v[98:101], v[90:93], v[8:11]
	v_mfma_f32_16x16x32_bf16 v[82:85], v[98:101], v[82:85], v[0:3]
	s_setprio 0
	s_nop 1
	ds_read_b128 v[0:3], v124 offset:16384
	ds_read_b128 v[8:11], v124 offset:18432
	ds_read_b128 v[12:15], v124 offset:20480
	ds_read_b128 v[86:89], v124 offset:22528
	ds_read_b128 v[98:101], v125 offset:49152
	ds_read_b128 v[164:167], v125 offset:51200
	ds_read_b128 v[168:171], v125 offset:53248
	ds_read_b128 v[172:175], v125 offset:55296
	s_setprio 1
	s_waitcnt lgkmcnt(3)
	v_mfma_f32_16x16x32_bf16 v[56:59], v[0:3], v[98:101], v[60:63]
	s_waitcnt lgkmcnt(2)
	v_mfma_f32_16x16x32_bf16 v[60:63], v[0:3], v[164:167], v[156:159]
	s_waitcnt lgkmcnt(1)
	v_mfma_f32_16x16x32_bf16 v[24:27], v[0:3], v[168:171], v[52:55]
	s_waitcnt lgkmcnt(0)
	v_mfma_f32_16x16x32_bf16 v[28:31], v[0:3], v[172:175], v[48:51]
	v_mfma_f32_16x16x32_bf16 v[52:55], v[8:11], v[98:101], v[44:47]
	v_mfma_f32_16x16x32_bf16 v[48:51], v[8:11], v[164:167], v[40:43]
	v_mfma_f32_16x16x32_bf16 v[16:19], v[8:11], v[168:171], v[36:39]
	v_mfma_f32_16x16x32_bf16 v[20:23], v[8:11], v[172:175], v[32:35]
	v_mfma_f32_16x16x32_bf16 v[40:43], v[12:15], v[98:101], v[148:151]
	v_mfma_f32_16x16x32_bf16 v[44:47], v[12:15], v[164:167], v[152:155]
	v_mfma_f32_16x16x32_bf16 v[8:11], v[12:15], v[168:171], v[160:163]
	v_mfma_f32_16x16x32_bf16 v[12:15], v[12:15], v[172:175], v[144:147]
	v_mfma_f32_16x16x32_bf16 v[32:35], v[86:89], v[98:101], v[94:97]
	v_mfma_f32_16x16x32_bf16 v[36:39], v[86:89], v[164:167], v[90:93]
	v_mfma_f32_16x16x32_bf16 v[0:3], v[86:89], v[168:171], v[4:7]
	v_mfma_f32_16x16x32_bf16 v[4:7], v[86:89], v[172:175], v[82:85]
	s_setprio 0
	s_waitcnt vmcnt(0)
	s_cmpk_lt_i32 s9, 0x80
	s_cselect_b64 s[42:43], -1, 0
	s_cmpk_gt_i32 s9, 0x7f
	s_mov_b64 s[0:1], -1
	s_barrier
	s_cbranch_scc0 .LBB0_904
	s_and_b32 s10, s20, 0x80
	s_cbranch_execz .LBB0_905

.LBB0_1239:
	s_setprio 3
	s_and_b32 s9, s8, 0x2000
	s_xor_b32 s18, s9, 0x2000
	s_lshl_b32 s101, s18, 1
	s_add_u32 s101, s101, s100
	s_add_u32 m0, s101, 0x0
	s_nop 0
	global_load_lds_dwordx4 v[184:185], off
	s_add_u32 m0, s101, 0x1000
	v_lshl_add_u64 v[184:185], v[184:185], 0, vcc
	global_load_lds_dwordx4 v[186:187], off
	s_add_u32 m0, s101, 0x2000
	v_lshl_add_u64 v[186:187], v[186:187], 0, vcc
	global_load_lds_dwordx4 v[188:189], off
	s_add_u32 m0, s101, 0x3000
	v_lshl_add_u64 v[188:189], v[188:189], 0, vcc
	global_load_lds_dwordx4 v[190:191], off
	s_add_u32 m0, s101, 0x8000
	v_lshl_add_u64 v[190:191], v[190:191], 0, vcc
	global_load_lds_dwordx4 v[192:193], off
	s_add_u32 m0, s101, 0x9000
	v_lshl_add_u64 v[192:193], v[192:193], 0, vcc
	global_load_lds_dwordx4 v[194:195], off
	s_add_u32 m0, s101, 0xa000
	v_lshl_add_u64 v[194:195], v[194:195], 0, vcc
	global_load_lds_dwordx4 v[196:197], off
	s_add_u32 m0, s101, 0xb000
	v_lshl_add_u64 v[196:197], v[196:197], 0, vcc
	global_load_lds_dwordx4 v[198:199], off
	s_setprio 0
	v_lshl_add_u64 v[198:199], v[198:199], 0, vcc
	s_lshl_b32 s9, s9, 1
	v_add_u32_e32 v136, s9, v84
	v_add_u32_e32 v137, s9, v83
	v_add_u32_e32 v100, v136, v86
	v_add_u32_e32 v132, v137, v86
	ds_read_b128 v[88:91], v100
	ds_read_b128 v[92:95], v100 offset:2048
	ds_read_b128 v[96:99], v100 offset:4096
	ds_read_b128 v[100:103], v100 offset:6144
	ds_read_b128 v[120:123], v132 offset:32768
	ds_read_b128 v[124:127], v132 offset:34816
	ds_read_b128 v[128:131], v132 offset:36864
	ds_read_b128 v[132:135], v132 offset:38912
	s_setprio 1
	s_waitcnt lgkmcnt(0)
	v_mfma_f32_16x16x32_bf16 v[60:63], v[120:123], v[88:91], v[60:63]
	v_mfma_f32_16x16x32_bf16 v[56:59], v[124:127], v[88:91], v[56:59]
	v_mfma_f32_16x16x32_bf16 v[52:55], v[128:131], v[88:91], v[52:55]
	v_mfma_f32_16x16x32_bf16 v[48:51], v[132:135], v[88:91], v[48:51]
	v_mfma_f32_16x16x32_bf16 v[44:47], v[120:123], v[92:95], v[44:47]
	v_mfma_f32_16x16x32_bf16 v[40:43], v[124:127], v[92:95], v[40:43]
	v_mfma_f32_16x16x32_bf16 v[36:39], v[128:131], v[92:95], v[36:39]
	v_mfma_f32_16x16x32_bf16 v[32:35], v[132:135], v[92:95], v[32:35]
	v_mfma_f32_16x16x32_bf16 v[28:31], v[120:123], v[96:99], v[28:31]
	v_mfma_f32_16x16x32_bf16 v[24:27], v[124:127], v[96:99], v[24:27]
	v_mfma_f32_16x16x32_bf16 v[20:23], v[128:131], v[96:99], v[20:23]
	v_mfma_f32_16x16x32_bf16 v[16:19], v[132:135], v[96:99], v[16:19]
	v_mfma_f32_16x16x32_bf16 v[12:15], v[120:123], v[100:103], v[12:15]
	v_mfma_f32_16x16x32_bf16 v[8:11], v[124:127], v[100:103], v[8:11]
	v_mfma_f32_16x16x32_bf16 v[4:7], v[128:131], v[100:103], v[4:7]
	v_mfma_f32_16x16x32_bf16 v[0:3], v[132:135], v[100:103], v[0:3]
	s_setprio 0
	v_add_u32_e32 v100, v136, v87
	v_add_u32_e32 v132, v137, v87
	ds_read_b128 v[88:91], v100
	ds_read_b128 v[92:95], v100 offset:2048
	ds_read_b128 v[96:99], v100 offset:4096
	ds_read_b128 v[100:103], v100 offset:6144
	ds_read_b128 v[120:123], v132 offset:32768
	ds_read_b128 v[124:127], v132 offset:34816
	ds_read_b128 v[128:131], v132 offset:36864
	ds_read_b128 v[132:135], v132 offset:38912
	s_setprio 1
	s_waitcnt lgkmcnt(0)
	v_mfma_f32_16x16x32_bf16 v[60:63], v[120:123], v[88:91], v[60:63]
	v_mfma_f32_16x16x32_bf16 v[56:59], v[124:127], v[88:91], v[56:59]
	v_mfma_f32_16x16x32_bf16 v[52:55], v[128:131], v[88:91], v[52:55]
	v_mfma_f32_16x16x32_bf16 v[48:51], v[132:135], v[88:91], v[48:51]
	v_mfma_f32_16x16x32_bf16 v[44:47], v[120:123], v[92:95], v[44:47]
	v_mfma_f32_16x16x32_bf16 v[40:43], v[124:127], v[92:95], v[40:43]
	v_mfma_f32_16x16x32_bf16 v[36:39], v[128:131], v[92:95], v[36:39]
	v_mfma_f32_16x16x32_bf16 v[32:35], v[132:135], v[92:95], v[32:35]
	v_mfma_f32_16x16x32_bf16 v[28:31], v[120:123], v[96:99], v[28:31]
	v_mfma_f32_16x16x32_bf16 v[24:27], v[124:127], v[96:99], v[24:27]
	v_mfma_f32_16x16x32_bf16 v[20:23], v[128:131], v[96:99], v[20:23]
	v_mfma_f32_16x16x32_bf16 v[16:19], v[132:135], v[96:99], v[16:19]
	v_mfma_f32_16x16x32_bf16 v[12:15], v[120:123], v[100:103], v[12:15]
	v_mfma_f32_16x16x32_bf16 v[8:11], v[124:127], v[100:103], v[8:11]
	v_mfma_f32_16x16x32_bf16 v[4:7], v[128:131], v[100:103], v[4:7]
	v_mfma_f32_16x16x32_bf16 v[0:3], v[132:135], v[100:103], v[0:3]
	s_setprio 0
	s_waitcnt vmcnt(0)
	s_add_u32 s20, s20, 0x80
	s_addc_u32 s21, s21, 0
	s_addk_i32 s8, 0x2000
	s_cmp_lg_u32 s1, s20
	s_waitcnt vmcnt(0)
	s_barrier
	s_cbranch_scc1 .LBB0_1239
	s_lshl_b32 s1, s36, 14
	s_addk_i32 s1, 0x4000
	s_and_b32 s1, s1, 0x4000
	v_add_u32_e32 v132, s1, v84
	v_add_u32_e32 v133, s1, v83
	v_add_u32_e32 v96, v132, v86
	v_add_u32_e32 v128, v133, v86
	ds_read_b128 v[78:81], v96
	ds_read_b128 v[88:91], v96 offset:2048
	ds_read_b128 v[92:95], v96 offset:4096
	ds_read_b128 v[96:99], v96 offset:6144
	ds_read_b128 v[100:103], v128 offset:32768
	ds_read_b128 v[120:123], v128 offset:34816
	ds_read_b128 v[124:127], v128 offset:36864
	ds_read_b128 v[128:131], v128 offset:38912
	s_setprio 1
	s_waitcnt lgkmcnt(3)
	v_mfma_f32_16x16x32_bf16 v[60:63], v[100:103], v[78:81], v[60:63]
	s_waitcnt lgkmcnt(2)
	v_mfma_f32_16x16x32_bf16 v[56:59], v[120:123], v[78:81], v[56:59]
	s_waitcnt lgkmcnt(1)
	v_mfma_f32_16x16x32_bf16 v[52:55], v[124:127], v[78:81], v[52:55]
	s_waitcnt lgkmcnt(0)
	v_mfma_f32_16x16x32_bf16 v[48:51], v[128:131], v[78:81], v[48:51]
	v_mfma_f32_16x16x32_bf16 v[44:47], v[100:103], v[88:91], v[44:47]
	v_mfma_f32_16x16x32_bf16 v[40:43], v[120:123], v[88:91], v[40:43]
	v_mfma_f32_16x16x32_bf16 v[36:39], v[124:127], v[88:91], v[36:39]
	v_mfma_f32_16x16x32_bf16 v[32:35], v[128:131], v[88:91], v[32:35]
	v_mfma_f32_16x16x32_bf16 v[28:31], v[100:103], v[92:95], v[28:31]
	v_mfma_f32_16x16x32_bf16 v[24:27], v[120:123], v[92:95], v[24:27]
	v_mfma_f32_16x16x32_bf16 v[20:23], v[124:127], v[92:95], v[20:23]
	v_mfma_f32_16x16x32_bf16 v[16:19], v[128:131], v[92:95], v[16:19]
	v_mfma_f32_16x16x32_bf16 v[12:15], v[100:103], v[96:99], v[12:15]
	v_mfma_f32_16x16x32_bf16 v[8:11], v[120:123], v[96:99], v[8:11]
	v_mfma_f32_16x16x32_bf16 v[4:7], v[124:127], v[96:99], v[4:7]
	v_mfma_f32_16x16x32_bf16 v[0:3], v[128:131], v[96:99], v[0:3]
	s_setprio 0
	v_add_u32_e32 v96, v132, v87
	v_add_u32_e32 v128, v133, v87
	ds_read_b128 v[78:81], v96
	ds_read_b128 v[88:91], v96 offset:2048
	ds_read_b128 v[92:95], v96 offset:4096
	ds_read_b128 v[96:99], v96 offset:6144
	ds_read_b128 v[100:103], v128 offset:32768
	ds_read_b128 v[120:123], v128 offset:34816
	ds_read_b128 v[124:127], v128 offset:36864
	ds_read_b128 v[128:131], v128 offset:38912
	s_setprio 1
	s_waitcnt lgkmcnt(3)
	v_mfma_f32_16x16x32_bf16 v[60:63], v[100:103], v[78:81], v[60:63]
	s_waitcnt lgkmcnt(2)
	v_mfma_f32_16x16x32_bf16 v[56:59], v[120:123], v[78:81], v[56:59]
	s_waitcnt lgkmcnt(1)
	v_mfma_f32_16x16x32_bf16 v[52:55], v[124:127], v[78:81], v[52:55]
	s_waitcnt lgkmcnt(0)
	v_mfma_f32_16x16x32_bf16 v[48:51], v[128:131], v[78:81], v[48:51]
	v_mfma_f32_16x16x32_bf16 v[44:47], v[100:103], v[88:91], v[44:47]
	v_mfma_f32_16x16x32_bf16 v[40:43], v[120:123], v[88:91], v[40:43]
	v_mfma_f32_16x16x32_bf16 v[36:39], v[124:127], v[88:91], v[36:39]
	v_mfma_f32_16x16x32_bf16 v[32:35], v[128:131], v[88:91], v[32:35]
	v_mfma_f32_16x16x32_bf16 v[28:31], v[100:103], v[92:95], v[28:31]
	v_mfma_f32_16x16x32_bf16 v[24:27], v[120:123], v[92:95], v[24:27]
	v_mfma_f32_16x16x32_bf16 v[20:23], v[124:127], v[92:95], v[20:23]
	v_mfma_f32_16x16x32_bf16 v[16:19], v[128:131], v[92:95], v[16:19]
	v_mfma_f32_16x16x32_bf16 v[12:15], v[100:103], v[96:99], v[12:15]
	v_mfma_f32_16x16x32_bf16 v[8:11], v[120:123], v[96:99], v[8:11]
	v_mfma_f32_16x16x32_bf16 v[4:7], v[124:127], v[96:99], v[4:7]
	v_mfma_f32_16x16x32_bf16 v[0:3], v[128:131], v[96:99], v[0:3]
	s_setprio 0
	s_lshl_b32 s1, s25, 3
	s_lshl_b32 s8, s11, 1
	s_or_b32 s1, s8, s1
	s_or_b32 s1, s1, s13
	s_lshl_b32 s1, s1, 4
	s_or_b32 s8, s1, s24
	s_ashr_i32 s9, s8, 31
	s_lshl_b64 s[8:9], s[8:9], 18
	s_add_u32 s8, s52, s8
	v_add_lshl_u32 v78, s10, v71, 8
	s_addc_u32 s9, s53, s9
	v_or_b32_e32 v80, s0, v85
	v_ashrrev_i32_e32 v79, 31, v78
	v_lshl_add_u64 v[78:79], v[78:79], 1, s[8:9]
	v_cvt_pk_bf16_f32 v60, v60, v61
	v_cvt_pk_bf16_f32 v61, v62, v63
	v_lshlrev_b32_e32 v62, 1, v80
	v_mov_b32_e32 v63, v69
	v_lshl_add_u64 v[80:81], v[78:79], 0, v[62:63]
	v_cvt_pk_bf16_f32 v48, v48, v49
	v_cvt_pk_bf16_f32 v49, v50, v51
	s_mov_b64 s[0:1], 0x2000
	s_waitcnt vmcnt(0)
	s_barrier
	global_store_dwordx2 v[80:81], v[48:49], off offset:96
	v_lshl_add_u64 v[48:49], v[78:79], 0, s[0:1]
	v_cvt_pk_bf16_f32 v44, v44, v45
	v_cvt_pk_bf16_f32 v45, v46, v47
	v_lshl_add_u64 v[46:47], v[48:49], 0, v[62:63]
	v_cvt_pk_bf16_f32 v40, v40, v41
	v_cvt_pk_bf16_f32 v41, v42, v43
	v_or_b32_e32 v42, 32, v62
	v_mov_b32_e32 v43, v69
	global_store_dwordx2 v[46:47], v[44:45], off
	v_lshl_add_u64 v[44:45], v[48:49], 0, v[42:43]
	v_cvt_pk_bf16_f32 v36, v36, v37
	v_cvt_pk_bf16_f32 v37, v38, v39
	v_or_b32_e32 v38, 64, v62
	v_mov_b32_e32 v39, v69
	global_store_dwordx2 v[44:45], v[40:41], off
	v_lshl_add_u64 v[40:41], v[48:49], 0, v[38:39]
	v_cvt_pk_bf16_f32 v32, v32, v33
	v_cvt_pk_bf16_f32 v33, v34, v35
	v_or_b32_e32 v34, 0x60, v62
	v_mov_b32_e32 v35, v69
	global_store_dwordx2 v[40:41], v[36:37], off
	v_lshl_add_u64 v[36:37], v[48:49], 0, v[34:35]
	s_mov_b64 s[0:1], 0x4000
	global_store_dwordx2 v[36:37], v[32:33], off
	v_lshl_add_u64 v[32:33], v[78:79], 0, s[0:1]
	v_cvt_pk_bf16_f32 v16, v16, v17
	v_cvt_pk_bf16_f32 v17, v18, v19
	v_lshl_add_u64 v[18:19], v[32:33], 0, v[34:35]
	s_mov_b64 s[0:1], 0x6000
	global_store_dwordx2 v[18:19], v[16:17], off
	v_lshl_add_u64 v[16:17], v[78:79], 0, s[0:1]
	v_readlane_b32 s0, v181, 50
	s_add_i32 s6, s6, s84
	s_add_i32 s12, s12, s0
	v_cvt_pk_bf16_f32 v56, v56, v57
	v_cvt_pk_bf16_f32 v57, v58, v59
	v_cvt_pk_bf16_f32 v52, v52, v53
	v_cvt_pk_bf16_f32 v53, v54, v55
	v_cvt_pk_bf16_f32 v28, v28, v29
	v_cvt_pk_bf16_f32 v29, v30, v31
	v_lshl_add_u64 v[30:31], v[32:33], 0, v[62:63]
	v_cvt_pk_bf16_f32 v24, v24, v25
	v_cvt_pk_bf16_f32 v25, v26, v27
	v_lshl_add_u64 v[26:27], v[32:33], 0, v[42:43]
	v_cvt_pk_bf16_f32 v20, v20, v21
	v_cvt_pk_bf16_f32 v21, v22, v23
	v_lshl_add_u64 v[22:23], v[32:33], 0, v[38:39]
	v_cvt_pk_bf16_f32 v12, v12, v13
	v_cvt_pk_bf16_f32 v13, v14, v15
	v_lshl_add_u64 v[14:15], v[16:17], 0, v[62:63]
	v_cvt_pk_bf16_f32 v8, v8, v9
	v_cvt_pk_bf16_f32 v9, v10, v11
	v_lshl_add_u64 v[10:11], v[16:17], 0, v[42:43]
	v_cvt_pk_bf16_f32 v4, v4, v5
	v_cvt_pk_bf16_f32 v5, v6, v7
	v_lshl_add_u64 v[6:7], v[16:17], 0, v[38:39]
	v_cvt_pk_bf16_f32 v0, v0, v1
	v_cvt_pk_bf16_f32 v1, v2, v3
	v_lshl_add_u64 v[2:3], v[16:17], 0, v[34:35]
	s_cmpk_lt_i32 s6, 0x800
	global_store_dwordx2 v[80:81], v[60:61], off
	global_store_dwordx2 v[80:81], v[56:57], off offset:32
	global_store_dwordx2 v[80:81], v[52:53], off offset:64
	global_store_dwordx2 v[30:31], v[28:29], off
	global_store_dwordx2 v[26:27], v[24:25], off
	global_store_dwordx2 v[22:23], v[20:21], off
	global_store_dwordx2 v[14:15], v[12:13], off
	global_store_dwordx2 v[10:11], v[8:9], off
	global_store_dwordx2 v[6:7], v[4:5], off
	global_store_dwordx2 v[2:3], v[0:1], off
	s_cbranch_scc1 .LBB0_1234
	v_readlane_b32 s50, v180, 0
	s_mov_b32 s18, 0x42ce8ed0
	s_mov_b32 s19, 0xc2b17218
	s_mov_b32 s48, s5
	v_readlane_b32 s51, v180, 1

.LBB0_1487:
	s_setprio 3
	s_and_b32 s6, s0, 0x2000
	s_xor_b32 s8, s6, 0x2000
	s_lshl_b32 s101, s8, 1
	s_add_u32 s101, s101, s100
	s_add_u32 m0, s101, 0x0
	s_nop 0
	global_load_lds_dwordx4 v[184:185], off
	s_add_u32 m0, s101, 0x1000
	v_lshl_add_u64 v[184:185], v[184:185], 0, vcc
	global_load_lds_dwordx4 v[186:187], off
	s_add_u32 m0, s101, 0x2000
	v_lshl_add_u64 v[186:187], v[186:187], 0, vcc
	global_load_lds_dwordx4 v[188:189], off
	s_add_u32 m0, s101, 0x3000
	v_lshl_add_u64 v[188:189], v[188:189], 0, vcc
	global_load_lds_dwordx4 v[190:191], off
	s_add_u32 m0, s101, 0x8000
	v_lshl_add_u64 v[190:191], v[190:191], 0, vcc
	global_load_lds_dwordx4 v[192:193], off
	s_add_u32 m0, s101, 0x9000
	v_lshl_add_u64 v[192:193], v[192:193], 0, vcc
	global_load_lds_dwordx4 v[194:195], off
	s_add_u32 m0, s101, 0xa000
	v_lshl_add_u64 v[194:195], v[194:195], 0, vcc
	global_load_lds_dwordx4 v[196:197], off
	s_add_u32 m0, s101, 0xb000
	v_lshl_add_u64 v[196:197], v[196:197], 0, vcc
	global_load_lds_dwordx4 v[198:199], off
	s_setprio 0
	v_lshl_add_u64 v[198:199], v[198:199], 0, vcc
	s_lshl_b32 s6, s6, 1
	v_add_u32_e32 v148, s6, v92
	v_add_u32_e32 v149, s6, v71
	v_add_u32_e32 v128, v148, v98
	v_add_u32_e32 v144, v149, v98
	ds_read_b128 v[100:103], v128
	ds_read_b128 v[120:123], v128 offset:2048
	ds_read_b128 v[124:127], v128 offset:4096
	ds_read_b128 v[128:131], v128 offset:6144
	ds_read_b128 v[132:135], v144 offset:32768
	ds_read_b128 v[136:139], v144 offset:34816
	ds_read_b128 v[140:143], v144 offset:36864
	ds_read_b128 v[144:147], v144 offset:38912
	s_setprio 1
	s_waitcnt lgkmcnt(0)
	v_mfma_f32_16x16x32_bf16 v[60:63], v[132:135], v[100:103], v[60:63]
	v_mfma_f32_16x16x32_bf16 v[56:59], v[136:139], v[100:103], v[56:59]
	v_mfma_f32_16x16x32_bf16 v[52:55], v[140:143], v[100:103], v[52:55]
	v_mfma_f32_16x16x32_bf16 v[48:51], v[144:147], v[100:103], v[48:51]
	v_mfma_f32_16x16x32_bf16 v[44:47], v[132:135], v[120:123], v[44:47]
	v_mfma_f32_16x16x32_bf16 v[40:43], v[136:139], v[120:123], v[40:43]
	v_mfma_f32_16x16x32_bf16 v[36:39], v[140:143], v[120:123], v[36:39]
	v_mfma_f32_16x16x32_bf16 v[32:35], v[144:147], v[120:123], v[32:35]
	v_mfma_f32_16x16x32_bf16 v[28:31], v[132:135], v[124:127], v[28:31]
	v_mfma_f32_16x16x32_bf16 v[24:27], v[136:139], v[124:127], v[24:27]
	v_mfma_f32_16x16x32_bf16 v[20:23], v[140:143], v[124:127], v[20:23]
	v_mfma_f32_16x16x32_bf16 v[16:19], v[144:147], v[124:127], v[16:19]
	v_mfma_f32_16x16x32_bf16 v[12:15], v[132:135], v[128:131], v[12:15]
	v_mfma_f32_16x16x32_bf16 v[8:11], v[136:139], v[128:131], v[8:11]
	v_mfma_f32_16x16x32_bf16 v[4:7], v[140:143], v[128:131], v[4:7]
	v_mfma_f32_16x16x32_bf16 v[0:3], v[144:147], v[128:131], v[0:3]
	s_setprio 0
	v_add_u32_e32 v128, v148, v99
	v_add_u32_e32 v144, v149, v99
	ds_read_b128 v[100:103], v128
	ds_read_b128 v[120:123], v128 offset:2048
	ds_read_b128 v[124:127], v128 offset:4096
	ds_read_b128 v[128:131], v128 offset:6144
	ds_read_b128 v[132:135], v144 offset:32768
	ds_read_b128 v[136:139], v144 offset:34816
	ds_read_b128 v[140:143], v144 offset:36864
	ds_read_b128 v[144:147], v144 offset:38912
	s_setprio 1
	s_waitcnt lgkmcnt(0)
	v_mfma_f32_16x16x32_bf16 v[60:63], v[132:135], v[100:103], v[60:63]
	v_mfma_f32_16x16x32_bf16 v[56:59], v[136:139], v[100:103], v[56:59]
	v_mfma_f32_16x16x32_bf16 v[52:55], v[140:143], v[100:103], v[52:55]
	v_mfma_f32_16x16x32_bf16 v[48:51], v[144:147], v[100:103], v[48:51]
	v_mfma_f32_16x16x32_bf16 v[44:47], v[132:135], v[120:123], v[44:47]
	v_mfma_f32_16x16x32_bf16 v[40:43], v[136:139], v[120:123], v[40:43]
	v_mfma_f32_16x16x32_bf16 v[36:39], v[140:143], v[120:123], v[36:39]
	v_mfma_f32_16x16x32_bf16 v[32:35], v[144:147], v[120:123], v[32:35]
	v_mfma_f32_16x16x32_bf16 v[28:31], v[132:135], v[124:127], v[28:31]
	v_mfma_f32_16x16x32_bf16 v[24:27], v[136:139], v[124:127], v[24:27]
	v_mfma_f32_16x16x32_bf16 v[20:23], v[140:143], v[124:127], v[20:23]
	v_mfma_f32_16x16x32_bf16 v[16:19], v[144:147], v[124:127], v[16:19]
	v_mfma_f32_16x16x32_bf16 v[12:15], v[132:135], v[128:131], v[12:15]
	v_mfma_f32_16x16x32_bf16 v[8:11], v[136:139], v[128:131], v[8:11]
	v_mfma_f32_16x16x32_bf16 v[4:7], v[140:143], v[128:131], v[4:7]
	v_mfma_f32_16x16x32_bf16 v[0:3], v[144:147], v[128:131], v[0:3]
	s_setprio 0
	s_waitcnt vmcnt(0)
	s_add_u32 s36, s36, 0x80
	s_addc_u32 s37, s37, 0
	s_addk_i32 s0, 0x2000
	s_cmpk_lg_i32 s36, 0xf80
	s_waitcnt vmcnt(0)
	s_barrier
	s_cbranch_scc1 .LBB0_1487
	ds_read_b128 v[88:91], v94 offset:16384
	ds_read_b128 v[100:103], v94 offset:18432
	ds_read_b128 v[120:123], v94 offset:20480
	ds_read_b128 v[124:127], v94 offset:22528
	ds_read_b128 v[128:131], v95 offset:49152
	ds_read_b128 v[132:135], v95 offset:51200
	ds_read_b128 v[136:139], v95 offset:53248
	ds_read_b128 v[140:143], v95 offset:55296
	s_setprio 1
	s_waitcnt lgkmcnt(3)
	v_mfma_f32_16x16x32_bf16 v[60:63], v[128:131], v[88:91], v[60:63]
	s_waitcnt lgkmcnt(2)
	v_mfma_f32_16x16x32_bf16 v[56:59], v[132:135], v[88:91], v[56:59]
	s_waitcnt lgkmcnt(1)
	v_mfma_f32_16x16x32_bf16 v[52:55], v[136:139], v[88:91], v[52:55]
	s_waitcnt lgkmcnt(0)
	v_mfma_f32_16x16x32_bf16 v[48:51], v[140:143], v[88:91], v[48:51]
	v_mfma_f32_16x16x32_bf16 v[40:43], v[132:135], v[100:103], v[40:43]
	v_mfma_f32_16x16x32_bf16 v[36:39], v[136:139], v[100:103], v[36:39]
	v_mfma_f32_16x16x32_bf16 v[32:35], v[140:143], v[100:103], v[32:35]
	v_mfma_f32_16x16x32_bf16 v[20:23], v[136:139], v[120:123], v[20:23]
	v_mfma_f32_16x16x32_bf16 v[16:19], v[140:143], v[120:123], v[16:19]
	v_mfma_f32_16x16x32_bf16 v[0:3], v[140:143], v[124:127], v[0:3]
	v_mfma_f32_16x16x32_bf16 v[88:91], v[128:131], v[100:103], v[44:47]
	v_mfma_f32_16x16x32_bf16 v[100:103], v[128:131], v[120:123], v[28:31]
	v_mfma_f32_16x16x32_bf16 v[144:147], v[132:135], v[120:123], v[24:27]
	v_mfma_f32_16x16x32_bf16 v[120:123], v[128:131], v[124:127], v[12:15]
	v_mfma_f32_16x16x32_bf16 v[128:131], v[132:135], v[124:127], v[8:11]
	v_mfma_f32_16x16x32_bf16 v[132:135], v[136:139], v[124:127], v[4:7]
	s_setprio 0
	s_nop 1
	ds_read_b128 v[4:7], v96 offset:16384
	ds_read_b128 v[8:11], v96 offset:18432
	ds_read_b128 v[124:127], v96 offset:20480
	ds_read_b128 v[136:139], v96 offset:22528
	ds_read_b128 v[140:143], v97 offset:49152
	ds_read_b128 v[148:151], v97 offset:51200
	ds_read_b128 v[152:155], v97 offset:53248
	ds_read_b128 v[156:159], v97 offset:55296
	s_setprio 1
	s_waitcnt lgkmcnt(3)
	v_mfma_f32_16x16x32_bf16 v[60:63], v[140:143], v[4:7], v[60:63]
	s_waitcnt lgkmcnt(2)
	v_mfma_f32_16x16x32_bf16 v[44:47], v[148:151], v[4:7], v[56:59]
	s_waitcnt lgkmcnt(1)
	v_mfma_f32_16x16x32_bf16 v[28:31], v[152:155], v[4:7], v[52:55]
	s_waitcnt lgkmcnt(0)
	v_mfma_f32_16x16x32_bf16 v[12:15], v[156:159], v[4:7], v[48:51]
	v_mfma_f32_16x16x32_bf16 v[56:59], v[140:143], v[8:11], v[88:91]
	v_mfma_f32_16x16x32_bf16 v[40:43], v[148:151], v[8:11], v[40:43]
	v_mfma_f32_16x16x32_bf16 v[24:27], v[152:155], v[8:11], v[36:39]
	v_mfma_f32_16x16x32_bf16 v[8:11], v[156:159], v[8:11], v[32:35]
	v_mfma_f32_16x16x32_bf16 v[52:55], v[140:143], v[124:127], v[100:103]
	v_mfma_f32_16x16x32_bf16 v[36:39], v[148:151], v[124:127], v[144:147]
	v_mfma_f32_16x16x32_bf16 v[20:23], v[152:155], v[124:127], v[20:23]
	v_mfma_f32_16x16x32_bf16 v[4:7], v[156:159], v[124:127], v[16:19]
	v_mfma_f32_16x16x32_bf16 v[48:51], v[140:143], v[136:139], v[120:123]
	v_mfma_f32_16x16x32_bf16 v[32:35], v[148:151], v[136:139], v[128:131]
	v_mfma_f32_16x16x32_bf16 v[16:19], v[152:155], v[136:139], v[132:135]
	v_mfma_f32_16x16x32_bf16 v[0:3], v[156:159], v[136:139], v[0:3]
	s_setprio 0
	s_waitcnt vmcnt(0)
	s_cmpk_gt_i32 s1, 0x7f
	s_barrier
	s_cbranch_scc0 .LBB0_1490
	s_add_i32 s0, s24, 0xffffc000
	s_lshr_b32 s0, s0, 8
	v_readlane_b32 s6, v180, 24
	s_add_i32 s6, s0, s6
	s_and_b32 s10, s24, 0x80
	s_lshl_b64 s[8:9], s[6:7], 8
	v_readlane_b32 s36, v182, 19
	s_or_b32 s8, s8, s10
	s_mov_b64 s[10:11], 0
	v_readlane_b32 s37, v182, 20
	s_branch .LBB0_1491

.LBB0_1498:
	s_setprio 3
	s_and_b32 s10, s6, 0x2000
	s_xor_b32 s8, s10, 0x2000
	s_lshl_b32 s101, s8, 1
	s_add_u32 s101, s101, s100
	s_add_u32 m0, s101, 0x0
	s_nop 0
	global_load_lds_dwordx4 v[184:185], off
	s_add_u32 m0, s101, 0x1000
	v_lshl_add_u64 v[184:185], v[184:185], 0, vcc
	global_load_lds_dwordx4 v[186:187], off
	s_add_u32 m0, s101, 0x2000
	v_lshl_add_u64 v[186:187], v[186:187], 0, vcc
	global_load_lds_dwordx4 v[188:189], off
	s_add_u32 m0, s101, 0x3000
	v_lshl_add_u64 v[188:189], v[188:189], 0, vcc
	global_load_lds_dwordx4 v[190:191], off
	s_add_u32 m0, s101, 0x8000
	v_lshl_add_u64 v[190:191], v[190:191], 0, vcc
	global_load_lds_dwordx4 v[192:193], off
	s_add_u32 m0, s101, 0x9000
	v_lshl_add_u64 v[192:193], v[192:193], 0, vcc
	global_load_lds_dwordx4 v[194:195], off
	s_add_u32 m0, s101, 0xa000
	v_lshl_add_u64 v[194:195], v[194:195], 0, vcc
	global_load_lds_dwordx4 v[196:197], off
	s_add_u32 m0, s101, 0xb000
	v_lshl_add_u64 v[196:197], v[196:197], 0, vcc
	global_load_lds_dwordx4 v[198:199], off
	s_setprio 0
	v_lshl_add_u64 v[198:199], v[198:199], 0, vcc
	s_lshl_b32 s8, s10, 1
	v_add_u32_e32 v68, s8, v84
	v_add_u32_e32 v140, s8, v83
	v_add_u32_e32 v120, v68, v90
	v_add_u32_e32 v136, v140, v90
	ds_read_b128 v[92:95], v120
	ds_read_b128 v[96:99], v120 offset:2048
	ds_read_b128 v[100:103], v120 offset:4096
	ds_read_b128 v[120:123], v120 offset:6144
	ds_read_b128 v[124:127], v136 offset:32768
	ds_read_b128 v[128:131], v136 offset:34816
	ds_read_b128 v[132:135], v136 offset:36864
	ds_read_b128 v[136:139], v136 offset:38912
	s_setprio 1
	s_waitcnt lgkmcnt(0)
	v_mfma_f32_16x16x32_bf16 v[60:63], v[124:127], v[92:95], v[60:63]
	v_mfma_f32_16x16x32_bf16 v[56:59], v[128:131], v[92:95], v[56:59]
	v_mfma_f32_16x16x32_bf16 v[52:55], v[132:135], v[92:95], v[52:55]
	v_mfma_f32_16x16x32_bf16 v[48:51], v[136:139], v[92:95], v[48:51]
	v_mfma_f32_16x16x32_bf16 v[44:47], v[124:127], v[96:99], v[44:47]
	v_mfma_f32_16x16x32_bf16 v[40:43], v[128:131], v[96:99], v[40:43]
	v_mfma_f32_16x16x32_bf16 v[36:39], v[132:135], v[96:99], v[36:39]
	v_mfma_f32_16x16x32_bf16 v[32:35], v[136:139], v[96:99], v[32:35]
	v_mfma_f32_16x16x32_bf16 v[28:31], v[124:127], v[100:103], v[28:31]
	v_mfma_f32_16x16x32_bf16 v[24:27], v[128:131], v[100:103], v[24:27]
	v_mfma_f32_16x16x32_bf16 v[20:23], v[132:135], v[100:103], v[20:23]
	v_mfma_f32_16x16x32_bf16 v[16:19], v[136:139], v[100:103], v[16:19]
	v_mfma_f32_16x16x32_bf16 v[12:15], v[124:127], v[120:123], v[12:15]
	v_mfma_f32_16x16x32_bf16 v[8:11], v[128:131], v[120:123], v[8:11]
	v_mfma_f32_16x16x32_bf16 v[4:7], v[132:135], v[120:123], v[4:7]
	v_mfma_f32_16x16x32_bf16 v[0:3], v[136:139], v[120:123], v[0:3]
	s_setprio 0
	v_add_u32_e32 v68, v68, v91
	ds_read_b128 v[92:95], v68
	ds_read_b128 v[96:99], v68 offset:2048
	ds_read_b128 v[100:103], v68 offset:4096
	ds_read_b128 v[120:123], v68 offset:6144
	v_add_u32_e32 v68, v140, v91
	ds_read_b128 v[124:127], v68 offset:32768
	ds_read_b128 v[128:131], v68 offset:34816
	ds_read_b128 v[132:135], v68 offset:36864
	ds_read_b128 v[136:139], v68 offset:38912
	s_setprio 1
	s_waitcnt lgkmcnt(0)
	v_mfma_f32_16x16x32_bf16 v[60:63], v[124:127], v[92:95], v[60:63]
	v_mfma_f32_16x16x32_bf16 v[56:59], v[128:131], v[92:95], v[56:59]
	v_mfma_f32_16x16x32_bf16 v[52:55], v[132:135], v[92:95], v[52:55]
	v_mfma_f32_16x16x32_bf16 v[48:51], v[136:139], v[92:95], v[48:51]
	v_mfma_f32_16x16x32_bf16 v[44:47], v[124:127], v[96:99], v[44:47]
	v_mfma_f32_16x16x32_bf16 v[40:43], v[128:131], v[96:99], v[40:43]
	v_mfma_f32_16x16x32_bf16 v[36:39], v[132:135], v[96:99], v[36:39]
	v_mfma_f32_16x16x32_bf16 v[32:35], v[136:139], v[96:99], v[32:35]
	v_mfma_f32_16x16x32_bf16 v[28:31], v[124:127], v[100:103], v[28:31]
	v_mfma_f32_16x16x32_bf16 v[24:27], v[128:131], v[100:103], v[24:27]
	v_mfma_f32_16x16x32_bf16 v[20:23], v[132:135], v[100:103], v[20:23]
	v_mfma_f32_16x16x32_bf16 v[16:19], v[136:139], v[100:103], v[16:19]
	v_mfma_f32_16x16x32_bf16 v[12:15], v[124:127], v[120:123], v[12:15]
	v_mfma_f32_16x16x32_bf16 v[8:11], v[128:131], v[120:123], v[8:11]
	v_mfma_f32_16x16x32_bf16 v[4:7], v[132:135], v[120:123], v[4:7]
	v_mfma_f32_16x16x32_bf16 v[0:3], v[136:139], v[120:123], v[0:3]
	s_setprio 0
	s_addk_i32 s6, 0x2000
	s_waitcnt vmcnt(0)
	s_add_u32 s36, s36, 0x80
	s_addc_u32 s37, s37, 0
	s_cmpk_lg_i32 s36, 0x780
	s_waitcnt vmcnt(0)
	s_barrier
	s_cbranch_scc1 .LBB0_1498
	ds_read_b128 v[78:81], v85 offset:55296
	ds_read_b128 v[92:95], v85 offset:53248
	ds_read_b128 v[96:99], v85 offset:51200
	ds_read_b128 v[100:103], v85 offset:49152
	ds_read_b128 v[120:123], v86 offset:22528
	ds_read_b128 v[124:127], v86 offset:20480
	ds_read_b128 v[128:131], v86 offset:18432
	ds_read_b128 v[132:135], v86 offset:16384
	s_setprio 1
	s_waitcnt lgkmcnt(0)
	v_mfma_f32_16x16x32_bf16 v[60:63], v[100:103], v[132:135], v[60:63]
	v_mfma_f32_16x16x32_bf16 v[56:59], v[96:99], v[132:135], v[56:59]
	v_mfma_f32_16x16x32_bf16 v[52:55], v[92:95], v[132:135], v[52:55]
	v_mfma_f32_16x16x32_bf16 v[48:51], v[78:81], v[132:135], v[48:51]
	v_mfma_f32_16x16x32_bf16 v[44:47], v[100:103], v[128:131], v[44:47]
	v_mfma_f32_16x16x32_bf16 v[40:43], v[96:99], v[128:131], v[40:43]
	v_mfma_f32_16x16x32_bf16 v[36:39], v[92:95], v[128:131], v[36:39]
	v_mfma_f32_16x16x32_bf16 v[32:35], v[78:81], v[128:131], v[32:35]
	v_mfma_f32_16x16x32_bf16 v[28:31], v[100:103], v[124:127], v[28:31]
	v_mfma_f32_16x16x32_bf16 v[24:27], v[96:99], v[124:127], v[24:27]
	v_mfma_f32_16x16x32_bf16 v[20:23], v[92:95], v[124:127], v[20:23]
	v_mfma_f32_16x16x32_bf16 v[16:19], v[78:81], v[124:127], v[16:19]
	v_mfma_f32_16x16x32_bf16 v[12:15], v[100:103], v[120:123], v[12:15]
	v_mfma_f32_16x16x32_bf16 v[8:11], v[96:99], v[120:123], v[8:11]
	v_mfma_f32_16x16x32_bf16 v[4:7], v[92:95], v[120:123], v[4:7]
	v_mfma_f32_16x16x32_bf16 v[0:3], v[78:81], v[120:123], v[0:3]
	s_setprio 0
	ds_read_b128 v[78:81], v87 offset:16384
	ds_read_b128 v[92:95], v87 offset:18432
	ds_read_b128 v[96:99], v87 offset:20480
	ds_read_b128 v[100:103], v87 offset:22528
	ds_read_b128 v[120:123], v88 offset:49152
	ds_read_b128 v[124:127], v88 offset:51200
	ds_read_b128 v[128:131], v88 offset:53248
	ds_read_b128 v[132:135], v88 offset:55296
	s_setprio 1
	s_waitcnt lgkmcnt(3)
	v_mfma_f32_16x16x32_bf16 v[60:63], v[120:123], v[78:81], v[60:63]
	s_waitcnt lgkmcnt(2)
	v_mfma_f32_16x16x32_bf16 v[56:59], v[124:127], v[78:81], v[56:59]
	s_waitcnt lgkmcnt(1)
	v_mfma_f32_16x16x32_bf16 v[52:55], v[128:131], v[78:81], v[52:55]
	s_waitcnt lgkmcnt(0)
	v_mfma_f32_16x16x32_bf16 v[48:51], v[132:135], v[78:81], v[48:51]
	v_mfma_f32_16x16x32_bf16 v[44:47], v[120:123], v[92:95], v[44:47]
	v_mfma_f32_16x16x32_bf16 v[40:43], v[124:127], v[92:95], v[40:43]
	v_mfma_f32_16x16x32_bf16 v[36:39], v[128:131], v[92:95], v[36:39]
	v_mfma_f32_16x16x32_bf16 v[32:35], v[132:135], v[92:95], v[32:35]
	v_mfma_f32_16x16x32_bf16 v[28:31], v[120:123], v[96:99], v[28:31]
	v_mfma_f32_16x16x32_bf16 v[24:27], v[124:127], v[96:99], v[24:27]
	v_mfma_f32_16x16x32_bf16 v[20:23], v[128:131], v[96:99], v[20:23]
	v_mfma_f32_16x16x32_bf16 v[16:19], v[132:135], v[96:99], v[16:19]
	v_mfma_f32_16x16x32_bf16 v[12:15], v[120:123], v[100:103], v[12:15]
	v_mfma_f32_16x16x32_bf16 v[8:11], v[124:127], v[100:103], v[8:11]
	v_mfma_f32_16x16x32_bf16 v[4:7], v[128:131], v[100:103], v[4:7]
	v_mfma_f32_16x16x32_bf16 v[0:3], v[132:135], v[100:103], v[0:3]
	s_setprio 0
	s_ashr_i32 s1, s1, 4
	s_mul_hi_i32 s6, s1, 0x4200000
	s_mul_i32 s1, s1, 0x4200000
	s_add_u32 s8, s90, s1
	v_add_u32_e32 v78, s20, v71
	s_addc_u32 s9, s91, s6
	s_and_b32 s1, s24, 0x780
	v_ashrrev_i32_e32 v79, 31, v78
	v_or_b32_e32 v68, s1, v89
	v_lshlrev_b64 v[80:81], 12, v[78:79]
	v_lshl_add_u64 v[80:81], s[8:9], 0, v[80:81]
	v_lshlrev_b32_e32 v68, 1, v68
	v_cvt_pk_bf16_f32 v60, v60, v61
	v_cvt_pk_bf16_f32 v61, v62, v63
	v_lshl_add_u64 v[62:63], v[80:81], 0, v[68:69]
	v_cvt_pk_bf16_f32 v48, v48, v49
	v_cvt_pk_bf16_f32 v49, v50, v51
	s_waitcnt vmcnt(0)
	s_barrier
	global_store_dwordx2 v[62:63], v[48:49], off offset:96
	v_or_b32_e32 v48, 16, v78
	v_ashrrev_i32_e32 v49, 31, v48
	v_lshlrev_b64 v[48:49], 12, v[48:49]
	v_lshl_add_u64 v[48:49], s[8:9], 0, v[48:49]
	v_cvt_pk_bf16_f32 v44, v44, v45
	v_cvt_pk_bf16_f32 v45, v46, v47
	v_lshl_add_u64 v[46:47], v[48:49], 0, v[68:69]
	v_cvt_pk_bf16_f32 v32, v32, v33
	v_cvt_pk_bf16_f32 v33, v34, v35
	global_store_dwordx2 v[46:47], v[32:33], off offset:96
	v_or_b32_e32 v32, 32, v78
	v_ashrrev_i32_e32 v33, 31, v32
	v_lshlrev_b64 v[32:33], 12, v[32:33]
	v_lshl_add_u64 v[32:33], s[8:9], 0, v[32:33]
	v_cvt_pk_bf16_f32 v28, v28, v29
	v_cvt_pk_bf16_f32 v29, v30, v31
	v_lshl_add_u64 v[30:31], v[32:33], 0, v[68:69]
	v_cvt_pk_bf16_f32 v16, v16, v17
	v_cvt_pk_bf16_f32 v17, v18, v19
	global_store_dwordx2 v[30:31], v[16:17], off offset:96
	v_or_b32_e32 v16, 48, v78
	v_ashrrev_i32_e32 v17, 31, v16
	v_lshlrev_b64 v[16:17], 12, v[16:17]
	v_lshl_add_u64 v[16:17], s[8:9], 0, v[16:17]
	s_add_i32 s0, s0, s84
	v_cvt_pk_bf16_f32 v56, v56, v57
	v_cvt_pk_bf16_f32 v57, v58, v59
	v_cvt_pk_bf16_f32 v52, v52, v53
	v_cvt_pk_bf16_f32 v53, v54, v55
	v_cvt_pk_bf16_f32 v40, v40, v41
	v_cvt_pk_bf16_f32 v41, v42, v43
	v_cvt_pk_bf16_f32 v36, v36, v37
	v_cvt_pk_bf16_f32 v37, v38, v39
	v_cvt_pk_bf16_f32 v24, v24, v25
	v_cvt_pk_bf16_f32 v25, v26, v27
	v_cvt_pk_bf16_f32 v20, v20, v21
	v_cvt_pk_bf16_f32 v21, v22, v23
	v_cvt_pk_bf16_f32 v12, v12, v13
	v_cvt_pk_bf16_f32 v13, v14, v15
	v_lshl_add_u64 v[14:15], v[16:17], 0, v[68:69]
	v_cvt_pk_bf16_f32 v8, v8, v9
	v_cvt_pk_bf16_f32 v9, v10, v11
	v_cvt_pk_bf16_f32 v4, v4, v5
	v_cvt_pk_bf16_f32 v5, v6, v7
	v_cvt_pk_bf16_f32 v0, v0, v1
	v_cvt_pk_bf16_f32 v1, v2, v3
	s_cmpk_lt_i32 s0, 0x18c0
	global_store_dwordx2 v[62:63], v[60:61], off
	global_store_dwordx2 v[62:63], v[56:57], off offset:32
	global_store_dwordx2 v[62:63], v[52:53], off offset:64
	global_store_dwordx2 v[46:47], v[44:45], off
	global_store_dwordx2 v[46:47], v[40:41], off offset:32
	global_store_dwordx2 v[46:47], v[36:37], off offset:64
	global_store_dwordx2 v[30:31], v[28:29], off
	global_store_dwordx2 v[30:31], v[24:25], off offset:32
	global_store_dwordx2 v[30:31], v[20:21], off offset:64
	global_store_dwordx2 v[14:15], v[12:13], off
	global_store_dwordx2 v[14:15], v[8:9], off offset:32
	global_store_dwordx2 v[14:15], v[4:5], off offset:64
	global_store_dwordx2 v[14:15], v[0:1], off offset:96
	s_cbranch_scc1 .LBB0_1497

.LBB0_1707:
	s_setprio 3
	s_and_b32 s6, s0, 0x2000
	s_xor_b32 s8, s6, 0x2000
	s_lshl_b32 s101, s8, 1
	s_add_u32 s101, s101, s100
	s_add_u32 m0, s101, 0x0
	s_nop 0
	global_load_lds_dwordx4 v[184:185], off
	s_add_u32 m0, s101, 0x1000
	v_lshl_add_u64 v[184:185], v[184:185], 0, vcc
	global_load_lds_dwordx4 v[186:187], off
	s_add_u32 m0, s101, 0x2000
	v_lshl_add_u64 v[186:187], v[186:187], 0, vcc
	global_load_lds_dwordx4 v[188:189], off
	s_add_u32 m0, s101, 0x3000
	v_lshl_add_u64 v[188:189], v[188:189], 0, vcc
	global_load_lds_dwordx4 v[190:191], off
	s_add_u32 m0, s101, 0x8000
	v_lshl_add_u64 v[190:191], v[190:191], 0, vcc
	global_load_lds_dwordx4 v[192:193], off
	s_add_u32 m0, s101, 0x9000
	v_lshl_add_u64 v[192:193], v[192:193], 0, vcc
	global_load_lds_dwordx4 v[194:195], off
	s_add_u32 m0, s101, 0xa000
	v_lshl_add_u64 v[194:195], v[194:195], 0, vcc
	global_load_lds_dwordx4 v[196:197], off
	s_add_u32 m0, s101, 0xb000
	v_lshl_add_u64 v[196:197], v[196:197], 0, vcc
	global_load_lds_dwordx4 v[198:199], off
	s_setprio 0
	v_lshl_add_u64 v[198:199], v[198:199], 0, vcc
	s_lshl_b32 s6, s6, 1
	v_add_u32_e32 v102, s6, v90
	v_add_u32_e32 v103, s6, v71
	v_add_u32_e32 v128, v102, v96
	v_add_u32_e32 v144, v103, v96
	ds_read_b128 v[98:101], v128
	ds_read_b128 v[120:123], v128 offset:2048
	ds_read_b128 v[124:127], v128 offset:4096
	ds_read_b128 v[128:131], v128 offset:6144
	ds_read_b128 v[132:135], v144 offset:32768
	ds_read_b128 v[136:139], v144 offset:34816
	ds_read_b128 v[140:143], v144 offset:36864
	ds_read_b128 v[144:147], v144 offset:38912
	s_setprio 1
	s_waitcnt lgkmcnt(0)
	v_mfma_f32_16x16x32_bf16 v[60:63], v[132:135], v[98:101], v[60:63]
	v_mfma_f32_16x16x32_bf16 v[56:59], v[136:139], v[98:101], v[56:59]
	v_mfma_f32_16x16x32_bf16 v[52:55], v[140:143], v[98:101], v[52:55]
	v_mfma_f32_16x16x32_bf16 v[48:51], v[144:147], v[98:101], v[48:51]
	v_mfma_f32_16x16x32_bf16 v[44:47], v[132:135], v[120:123], v[44:47]
	v_mfma_f32_16x16x32_bf16 v[40:43], v[136:139], v[120:123], v[40:43]
	v_mfma_f32_16x16x32_bf16 v[36:39], v[140:143], v[120:123], v[36:39]
	v_mfma_f32_16x16x32_bf16 v[32:35], v[144:147], v[120:123], v[32:35]
	v_mfma_f32_16x16x32_bf16 v[28:31], v[132:135], v[124:127], v[28:31]
	v_mfma_f32_16x16x32_bf16 v[24:27], v[136:139], v[124:127], v[24:27]
	v_mfma_f32_16x16x32_bf16 v[20:23], v[140:143], v[124:127], v[20:23]
	v_mfma_f32_16x16x32_bf16 v[16:19], v[144:147], v[124:127], v[16:19]
	v_mfma_f32_16x16x32_bf16 v[12:15], v[132:135], v[128:131], v[12:15]
	v_mfma_f32_16x16x32_bf16 v[8:11], v[136:139], v[128:131], v[8:11]
	v_mfma_f32_16x16x32_bf16 v[4:7], v[140:143], v[128:131], v[4:7]
	v_mfma_f32_16x16x32_bf16 v[0:3], v[144:147], v[128:131], v[0:3]
	s_setprio 0
	v_add_u32_e32 v102, v102, v97
	ds_read_b128 v[98:101], v102
	ds_read_b128 v[120:123], v102 offset:2048
	ds_read_b128 v[124:127], v102 offset:4096
	ds_read_b128 v[128:131], v102 offset:6144
	v_add_u32_e32 v102, v103, v97
	ds_read_b128 v[132:135], v102 offset:32768
	ds_read_b128 v[136:139], v102 offset:34816
	ds_read_b128 v[140:143], v102 offset:36864
	ds_read_b128 v[144:147], v102 offset:38912
	s_setprio 1
	s_waitcnt lgkmcnt(0)
	v_mfma_f32_16x16x32_bf16 v[60:63], v[132:135], v[98:101], v[60:63]
	v_mfma_f32_16x16x32_bf16 v[56:59], v[136:139], v[98:101], v[56:59]
	v_mfma_f32_16x16x32_bf16 v[52:55], v[140:143], v[98:101], v[52:55]
	v_mfma_f32_16x16x32_bf16 v[48:51], v[144:147], v[98:101], v[48:51]
	v_mfma_f32_16x16x32_bf16 v[44:47], v[132:135], v[120:123], v[44:47]
	v_mfma_f32_16x16x32_bf16 v[40:43], v[136:139], v[120:123], v[40:43]
	v_mfma_f32_16x16x32_bf16 v[36:39], v[140:143], v[120:123], v[36:39]
	v_mfma_f32_16x16x32_bf16 v[32:35], v[144:147], v[120:123], v[32:35]
	v_mfma_f32_16x16x32_bf16 v[28:31], v[132:135], v[124:127], v[28:31]
	v_mfma_f32_16x16x32_bf16 v[24:27], v[136:139], v[124:127], v[24:27]
	v_mfma_f32_16x16x32_bf16 v[20:23], v[140:143], v[124:127], v[20:23]
	v_mfma_f32_16x16x32_bf16 v[16:19], v[144:147], v[124:127], v[16:19]
	v_mfma_f32_16x16x32_bf16 v[12:15], v[132:135], v[128:131], v[12:15]
	v_mfma_f32_16x16x32_bf16 v[8:11], v[136:139], v[128:131], v[8:11]
	v_mfma_f32_16x16x32_bf16 v[4:7], v[140:143], v[128:131], v[4:7]
	v_mfma_f32_16x16x32_bf16 v[0:3], v[144:147], v[128:131], v[0:3]
	s_setprio 0
	s_waitcnt vmcnt(0)
	s_add_u32 s36, s36, 0x80
	s_addc_u32 s37, s37, 0
	s_addk_i32 s0, 0x2000
	s_cmpk_lg_i32 s36, 0xf80
	s_waitcnt vmcnt(0)
	s_barrier
	s_cbranch_scc1 .LBB0_1707
	ds_read_b128 v[86:89], v92 offset:16384
	ds_read_b128 v[98:101], v92 offset:18432
	ds_read_b128 v[120:123], v92 offset:20480
	ds_read_b128 v[124:127], v92 offset:22528
	ds_read_b128 v[128:131], v93 offset:49152
	ds_read_b128 v[132:135], v93 offset:51200
	ds_read_b128 v[136:139], v93 offset:53248
	ds_read_b128 v[140:143], v93 offset:55296
	s_setprio 1
	s_waitcnt lgkmcnt(3)
	v_mfma_f32_16x16x32_bf16 v[60:63], v[128:131], v[86:89], v[60:63]
	s_waitcnt lgkmcnt(2)
	v_mfma_f32_16x16x32_bf16 v[56:59], v[132:135], v[86:89], v[56:59]
	s_waitcnt lgkmcnt(1)
	v_mfma_f32_16x16x32_bf16 v[52:55], v[136:139], v[86:89], v[52:55]
	s_waitcnt lgkmcnt(0)
	v_mfma_f32_16x16x32_bf16 v[48:51], v[140:143], v[86:89], v[48:51]
	v_mfma_f32_16x16x32_bf16 v[40:43], v[132:135], v[98:101], v[40:43]
	v_mfma_f32_16x16x32_bf16 v[36:39], v[136:139], v[98:101], v[36:39]
	v_mfma_f32_16x16x32_bf16 v[32:35], v[140:143], v[98:101], v[32:35]
	v_mfma_f32_16x16x32_bf16 v[20:23], v[136:139], v[120:123], v[20:23]
	v_mfma_f32_16x16x32_bf16 v[16:19], v[140:143], v[120:123], v[16:19]
	v_mfma_f32_16x16x32_bf16 v[0:3], v[140:143], v[124:127], v[0:3]
	v_mfma_f32_16x16x32_bf16 v[86:89], v[128:131], v[98:101], v[44:47]
	v_mfma_f32_16x16x32_bf16 v[98:101], v[128:131], v[120:123], v[28:31]
	v_mfma_f32_16x16x32_bf16 v[144:147], v[132:135], v[120:123], v[24:27]
	v_mfma_f32_16x16x32_bf16 v[120:123], v[128:131], v[124:127], v[12:15]
	v_mfma_f32_16x16x32_bf16 v[128:131], v[132:135], v[124:127], v[8:11]
	v_mfma_f32_16x16x32_bf16 v[132:135], v[136:139], v[124:127], v[4:7]
	s_setprio 0
	s_nop 1
	ds_read_b128 v[4:7], v94 offset:16384
	ds_read_b128 v[8:11], v94 offset:18432
	ds_read_b128 v[124:127], v94 offset:20480
	ds_read_b128 v[136:139], v94 offset:22528
	ds_read_b128 v[140:143], v95 offset:49152
	ds_read_b128 v[148:151], v95 offset:51200
	ds_read_b128 v[152:155], v95 offset:53248
	ds_read_b128 v[156:159], v95 offset:55296
	s_setprio 1
	s_waitcnt lgkmcnt(3)
	v_mfma_f32_16x16x32_bf16 v[60:63], v[140:143], v[4:7], v[60:63]
	s_waitcnt lgkmcnt(2)
	v_mfma_f32_16x16x32_bf16 v[44:47], v[148:151], v[4:7], v[56:59]
	s_waitcnt lgkmcnt(1)
	v_mfma_f32_16x16x32_bf16 v[28:31], v[152:155], v[4:7], v[52:55]
	s_waitcnt lgkmcnt(0)
	v_mfma_f32_16x16x32_bf16 v[12:15], v[156:159], v[4:7], v[48:51]
	v_mfma_f32_16x16x32_bf16 v[56:59], v[140:143], v[8:11], v[86:89]
	v_mfma_f32_16x16x32_bf16 v[40:43], v[148:151], v[8:11], v[40:43]
	v_mfma_f32_16x16x32_bf16 v[24:27], v[152:155], v[8:11], v[36:39]
	v_mfma_f32_16x16x32_bf16 v[8:11], v[156:159], v[8:11], v[32:35]
	v_mfma_f32_16x16x32_bf16 v[52:55], v[140:143], v[124:127], v[98:101]
	v_mfma_f32_16x16x32_bf16 v[36:39], v[148:151], v[124:127], v[144:147]
	v_mfma_f32_16x16x32_bf16 v[20:23], v[152:155], v[124:127], v[20:23]
	v_mfma_f32_16x16x32_bf16 v[4:7], v[156:159], v[124:127], v[16:19]
	v_mfma_f32_16x16x32_bf16 v[48:51], v[140:143], v[136:139], v[120:123]
	v_mfma_f32_16x16x32_bf16 v[32:35], v[148:151], v[136:139], v[128:131]
	v_mfma_f32_16x16x32_bf16 v[16:19], v[152:155], v[136:139], v[132:135]
	v_mfma_f32_16x16x32_bf16 v[0:3], v[156:159], v[136:139], v[0:3]
	s_setprio 0
	s_waitcnt vmcnt(0)
	s_cmpk_gt_i32 s1, 0x7f
	s_barrier
	s_cbranch_scc0 .LBB0_1710
	s_add_i32 s0, s24, 0xffffc000
	s_lshr_b32 s0, s0, 8
	v_readlane_b32 s6, v180, 24
	s_add_i32 s6, s0, s6
	s_and_b32 s10, s24, 0x80
	s_lshl_b64 s[8:9], s[6:7], 8
	v_readlane_b32 s36, v182, 19
	s_or_b32 s8, s8, s10
	s_mov_b64 s[10:11], 0
	v_readlane_b32 s37, v182, 20
	s_branch .LBB0_1711
